# ret_kv (phase 2): v^T / k^T tiles staged through a double-buffered LDS image (coalesced fills + ds_read fragments) instead of row-per-lane fragment loads
# speedup vs baseline: 1.0313x; 1.0137x over previous
.LBB0_689:
	v_readlane_b32 s0, v253, 16
	s_cmpk_gt_i32 s0, 0x81f
	s_cbranch_scc1 .LBB0_696
	v_lshlrev_b32_e32 v0, 6, v150
	v_lshl_add_u32 v70, s91, 7, v0
	s_movk_i32 s2, 0x7ff
	v_mov_b32_e32 v65, 0
	s_movk_i32 s3, 0xffc0
	v_readlane_b32 s4, v253, 16
	s_mov_b32 s98, 0
	s_branch .LBB0_692
.LBB0_691:
	s_or_b64 exec, exec, s[0:1]
	v_lshrrev_b32_e32 v200, 3, v67
	v_mul_u32_u24_e32 v201, v4, v200
	v_and_b32_e32 v202, 7, v67
	v_lshlrev_b32_e32 v201, 1, v201
	v_lshlrev_b32_e32 v202, 4, v202
	v_lshl_add_u32 v201, v6, 1, v201
	v_add_u32_e32 v202, v201, v202
	v_mov_b32_e32 v203, 0
	v_lshl_add_u64 v[204:205], v[0:1], 0, v[202:203]
	v_lshl_add_u64 v[206:207], v[2:3], 0, v[202:203]
	v_lshlrev_b32_e32 v208, 6, v4
	v_mov_b32_e32 v209, 0
	global_load_dwordx4 v[160:163], v[204:205], off
	global_load_dwordx4 v[176:179], v[206:207], off
	v_lshl_add_u64 v[204:205], v[204:205], 0, v[208:209]
	v_lshl_add_u64 v[206:207], v[206:207], 0, v[208:209]
	global_load_dwordx4 v[164:167], v[204:205], off
	global_load_dwordx4 v[180:183], v[206:207], off
	v_lshl_add_u64 v[204:205], v[204:205], 0, v[208:209]
	v_lshl_add_u64 v[206:207], v[206:207], 0, v[208:209]
	global_load_dwordx4 v[168:171], v[204:205], off
	global_load_dwordx4 v[184:187], v[206:207], off
	v_lshl_add_u64 v[204:205], v[204:205], 0, v[208:209]
	v_lshl_add_u64 v[206:207], v[206:207], 0, v[208:209]
	global_load_dwordx4 v[172:175], v[204:205], off
	global_load_dwordx4 v[188:191], v[206:207], off
	s_mul_i32 s99, s98, 0x9000
	v_mul_u32_u24_e32 v212, 0x14000, v150
	v_add_u32_e32 v212, s99, v212
	v_mul_u32_u24_e32 v210, 0x90, v200
	v_and_b32_e32 v211, 7, v67
	v_lshl_add_u32 v210, v211, 4, v210
	v_add_u32_e32 v210, v210, v212
	v_and_b32_e32 v213, 0x5f, v67
	v_mul_u32_u24_e32 v213, 0x90, v213
	v_bfe_u32 v211, v67, 5, 1
	v_lshl_add_u32 v213, v211, 4, v213
	v_add_u32_e32 v213, v213, v212
	v_ashrrev_i32_e32 v214, 1, v67
	v_and_b32_e32 v214, 0xffc0, v214
	v_and_b32_e32 v215, 31, v67
	v_or_b32_e32 v214, v214, v215
	v_mul_u32_u24_e32 v214, 0x90, v214
	v_lshl_add_u32 v214, v211, 4, v214
	v_add_u32_e32 v214, v214, v212
	v_add_u32_e32 v214, 0x4800, v214
	s_waitcnt vmcnt(0)
	ds_write_b128 v210, v[160:163]
	ds_write_b128 v210, v[164:167] offset:4608
	ds_write_b128 v210, v[168:171] offset:9216
	ds_write_b128 v210, v[172:175] offset:13824
	ds_write_b128 v210, v[176:179] offset:18432
	ds_write_b128 v210, v[180:183] offset:23040
	ds_write_b128 v210, v[184:187] offset:27648
	ds_write_b128 v210, v[188:191] offset:32256
	s_waitcnt lgkmcnt(0)
	s_barrier
	v_and_b32_e32 v18, 0x5f, v67
	v_and_b32_e32 v5, 31, v67
	v_ashrrev_i32_e32 v10, 1, v67
	v_mul_u32_u24_e32 v7, v4, v18
	v_lshlrev_b32_e32 v64, 1, v7
	v_and_or_b32 v102, v10, s3, v5
	v_bfe_u32 v71, v67, 5, 1
	v_lshl_add_u64 v[8:9], v[0:1], 0, v[64:65]
	v_lshlrev_b32_e32 v64, 1, v6
	v_or_b32_e32 v66, 32, v102
	v_lshl_add_u64 v[6:7], v[8:9], 0, v[64:65]
	v_lshlrev_b32_e32 v14, 4, v71
	v_mov_b32_e32 v15, v65
	v_mad_i64_i32 v[10:11], s[0:1], v4, v102, 0
	v_mad_i64_i32 v[16:17], s[0:1], v4, v66, 0
	v_lshl_add_u64 v[92:93], v[6:7], 0, v[14:15]
	v_lshl_add_u64 v[10:11], v[10:11], 1, v[2:3]
	v_lshl_add_u64 v[2:3], v[16:17], 1, v[2:3]
	ds_read_b128 v[6:9], v213
	v_lshl_add_u64 v[2:3], v[2:3], 0, v[64:65]
	v_lshl_add_u64 v[96:97], v[2:3], 0, v[14:15]
	v_or_b32_e32 v2, 32, v18
	v_lshl_add_u64 v[10:11], v[10:11], 0, v[64:65]
	v_mul_u32_u24_e32 v2, v4, v2
	v_lshl_add_u64 v[94:95], v[10:11], 0, v[14:15]
	v_mov_b32_e32 v3, v65
	v_lshlrev_b32_e32 v2, 1, v2
	ds_read_b128 v[10:13], v214
	ds_read_b128 v[72:75], v214 offset:4608
	v_lshl_add_u64 v[0:1], v[0:1], 0, v[2:3]
	v_lshl_add_u64 v[0:1], v[0:1], 0, v[64:65]
	v_lshl_add_u64 v[100:101], v[0:1], 0, v[14:15]
	ds_read_b128 v[76:79], v213 offset:32
	ds_read_b128 v[80:83], v214 offset:32
	ds_read_b128 v[0:3], v213 offset:4608
	ds_read_b128 v[84:87], v214 offset:4640
	ds_read_b128 v[88:91], v213 offset:4640
	v_lshlrev_b32_e32 v64, 7, v67
	v_and_b32_e32 v64, 0x2000, v64
	v_ashrrev_i32_e32 v69, 31, v68
	v_lshl_or_b32 v64, v71, 9, v64
	v_lshlrev_b64 v[68:69], 15, v[68:69]
	v_or_b32_e32 v71, 0x800, v64
	v_or_b32_e32 v103, 0x880, v64
	v_or_b32_e32 v104, 0x900, v64
	v_or_b32_e32 v105, 0x980, v64
	v_or_b32_e32 v106, 0xc00, v64
	v_or_b32_e32 v107, 0xc80, v64
	v_lshl_add_u64 v[68:69], s[88:89], 0, v[68:69]
	v_ashrrev_i32_e32 v67, 31, v66
	v_add_u32_e32 v70, 0x8000, v70
	s_waitcnt lgkmcnt(6)
	v_mfma_f32_32x32x16_bf16 v[48:63], v[6:9], v[10:13], 0
	s_waitcnt lgkmcnt(5)
	v_mfma_f32_32x32x16_bf16 v[32:47], v[6:9], v[72:75], 0
	s_waitcnt lgkmcnt(2)
	v_mfma_f32_32x32x16_bf16 v[16:31], v[0:3], v[10:13], 0
	v_mfma_f32_32x32x16_bf16 v[0:15], v[0:3], v[72:75], 0
	ds_read_b128 v[72:75], v213 offset:64
	v_mfma_f32_32x32x16_bf16 v[48:63], v[76:79], v[80:83], v[48:63]
	s_waitcnt lgkmcnt(2)
	v_mfma_f32_32x32x16_bf16 v[32:47], v[76:79], v[84:87], v[32:47]
	ds_read_b128 v[76:79], v214 offset:64
	s_waitcnt lgkmcnt(2)
	v_mfma_f32_32x32x16_bf16 v[16:31], v[88:91], v[80:83], v[16:31]
	v_mfma_f32_32x32x16_bf16 v[0:15], v[88:91], v[84:87], v[0:15]
	ds_read_b128 v[80:83], v214 offset:4672
	ds_read_b128 v[84:87], v213 offset:96
	ds_read_b128 v[88:91], v214 offset:96
	s_nop 0
	ds_read_b128 v[92:95], v213 offset:4672
	s_nop 0
	ds_read_b128 v[96:99], v214 offset:4704
	s_waitcnt lgkmcnt(4)
	v_mfma_f32_32x32x16_bf16 v[32:47], v[72:75], v[80:83], v[32:47]
	v_mfma_f32_32x32x16_bf16 v[48:63], v[72:75], v[76:79], v[48:63]
	ds_read_b128 v[72:75], v213 offset:4704
	v_add_u32_e32 v100, v107, v102
	v_ashrrev_i32_e32 v101, 31, v100
	s_waitcnt lgkmcnt(3)
	v_mfma_f32_32x32x16_bf16 v[48:63], v[84:87], v[88:91], v[48:63]
	s_waitcnt lgkmcnt(2)
	v_mfma_f32_32x32x16_bf16 v[16:31], v[92:95], v[76:79], v[16:31]
	v_add_u32_e32 v76, v64, v102
	v_ashrrev_i32_e32 v77, 31, v76
	v_add_u32_e32 v78, v71, v102
	v_lshl_add_u64 v[76:77], v[76:77], 1, v[68:69]
	v_ashrrev_i32_e32 v79, 31, v78
	s_nop 4
	v_cvt_pk_bf16_f32 v48, v48, s0
	v_cvt_pk_bf16_f32 v51, v51, s0
	v_mfma_f32_32x32x16_bf16 v[0:15], v[92:95], v[80:83], v[0:15]
	v_add_u32_e32 v80, v103, v102
	v_add_u32_e32 v82, v104, v102
	v_add_u32_e32 v92, v105, v102
	v_add_u32_e32 v94, v106, v102
	v_ashrrev_i32_e32 v81, 31, v80
	v_ashrrev_i32_e32 v83, 31, v82
	v_ashrrev_i32_e32 v93, 31, v92
	s_waitcnt lgkmcnt(1)
	v_mfma_f32_32x32x16_bf16 v[32:47], v[84:87], v[96:99], v[32:47]
	v_ashrrev_i32_e32 v95, 31, v94
	v_lshl_add_u64 v[78:79], v[78:79], 1, v[68:69]
	v_lshl_add_u64 v[80:81], v[80:81], 1, v[68:69]
	v_lshl_add_u64 v[82:83], v[82:83], 1, v[68:69]
	v_lshl_add_u64 v[84:85], v[92:93], 1, v[68:69]
	v_lshl_add_u64 v[86:87], v[94:95], 1, v[68:69]
	v_lshl_add_u64 v[92:93], v[100:101], 1, v[68:69]
	v_cvt_pk_bf16_f32 v49, v49, s0
	v_cvt_pk_bf16_f32 v50, v50, s0
	v_cvt_pk_bf16_f32 v52, v52, s0
	v_cvt_pk_bf16_f32 v53, v53, s0
	v_cvt_pk_bf16_f32 v54, v54, s0
	v_cvt_pk_bf16_f32 v55, v55, s0
	v_cvt_pk_bf16_f32 v56, v56, s0
	v_cvt_pk_bf16_f32 v57, v57, s0
	v_cvt_pk_bf16_f32 v58, v58, s0
	v_cvt_pk_bf16_f32 v59, v59, s0
	v_cvt_pk_bf16_f32 v60, v60, s0
	v_cvt_pk_bf16_f32 v61, v61, s0
	global_store_short v[76:77], v48, off
	global_store_short v[76:77], v49, off offset:256
	global_store_short v[76:77], v50, off offset:512
	global_store_short v[76:77], v51, off offset:768
	global_store_short v[76:77], v52, off offset:2048
	global_store_short v[76:77], v53, off offset:2304
	global_store_short v[76:77], v54, off offset:2560
	global_store_short v[76:77], v55, off offset:2816
	global_store_short v[78:79], v56, off
	global_store_short v[80:81], v57, off
	global_store_short v[82:83], v58, off
	global_store_short v[84:85], v59, off
	global_store_short v[86:87], v60, off
	global_store_short v[92:93], v61, off
	v_or_b32_e32 v51, 0xd00, v64
	v_add_u32_e32 v48, v51, v102
	v_ashrrev_i32_e32 v49, 31, v48
	v_cvt_pk_bf16_f32 v50, v62, s0
	v_lshl_add_u64 v[48:49], v[48:49], 1, v[68:69]
	v_or_b32_e32 v52, 0xd80, v64
	global_store_short v[48:49], v50, off
	v_add_u32_e32 v48, v52, v102
	v_ashrrev_i32_e32 v49, 31, v48
	v_cvt_pk_bf16_f32 v50, v63, s0
	v_lshl_add_u64 v[48:49], v[48:49], 1, v[68:69]
	v_cvt_pk_bf16_f32 v32, v32, s0
	global_store_short v[48:49], v50, off
	global_store_short v[76:77], v32, off offset:64
	v_cvt_pk_bf16_f32 v48, v33, s0
	v_lshl_add_u64 v[32:33], v[64:65], 0, v[66:67]
	v_lshl_add_u64 v[32:33], v[32:33], 1, v[68:69]
	v_cvt_pk_bf16_f32 v34, v34, s0
	global_store_short v[32:33], v34, off offset:512
	v_cvt_pk_bf16_f32 v34, v35, s0
	global_store_short v[32:33], v34, off offset:768
	v_cvt_pk_bf16_f32 v34, v36, s0
	global_store_short v[32:33], v34, off offset:2048
	v_cvt_pk_bf16_f32 v34, v37, s0
	global_store_short v[32:33], v34, off offset:2304
	v_cvt_pk_bf16_f32 v34, v38, s0
	global_store_short v[32:33], v34, off offset:2560
	v_cvt_pk_bf16_f32 v34, v39, s0
	global_store_short v[32:33], v48, off offset:256
	global_store_short v[32:33], v34, off offset:2816
	v_add_u32_e32 v32, v71, v66
	v_ashrrev_i32_e32 v33, 31, v32
	v_cvt_pk_bf16_f32 v34, v40, s0
	v_lshl_add_u64 v[32:33], v[32:33], 1, v[68:69]
	global_store_short v[32:33], v34, off
	v_add_u32_e32 v32, v103, v66
	v_ashrrev_i32_e32 v33, 31, v32
	v_cvt_pk_bf16_f32 v34, v41, s0
	v_lshl_add_u64 v[32:33], v[32:33], 1, v[68:69]
	global_store_short v[32:33], v34, off
	v_add_u32_e32 v32, v104, v66
	v_ashrrev_i32_e32 v33, 31, v32
	v_cvt_pk_bf16_f32 v34, v42, s0
	v_lshl_add_u64 v[32:33], v[32:33], 1, v[68:69]
	global_store_short v[32:33], v34, off
	v_add_u32_e32 v32, v105, v66
	v_ashrrev_i32_e32 v33, 31, v32
	v_cvt_pk_bf16_f32 v34, v43, s0
	v_lshl_add_u64 v[32:33], v[32:33], 1, v[68:69]
	global_store_short v[32:33], v34, off
	v_add_u32_e32 v32, v106, v66
	v_ashrrev_i32_e32 v33, 31, v32
	v_cvt_pk_bf16_f32 v34, v44, s0
	v_lshl_add_u64 v[32:33], v[32:33], 1, v[68:69]
	global_store_short v[32:33], v34, off
	v_add_u32_e32 v32, v107, v66
	v_ashrrev_i32_e32 v33, 31, v32
	v_cvt_pk_bf16_f32 v34, v45, s0
	v_lshl_add_u64 v[32:33], v[32:33], 1, v[68:69]
	global_store_short v[32:33], v34, off
	v_add_u32_e32 v32, v51, v66
	s_waitcnt lgkmcnt(0)
	v_mfma_f32_32x32x16_bf16 v[16:31], v[72:75], v[88:91], v[16:31]
	v_ashrrev_i32_e32 v33, 31, v32
	v_cvt_pk_bf16_f32 v34, v46, s0
	v_lshl_add_u64 v[32:33], v[32:33], 1, v[68:69]
	global_store_short v[32:33], v34, off
	v_add_u32_e32 v32, v52, v66
	v_ashrrev_i32_e32 v33, 31, v32
	v_cvt_pk_bf16_f32 v34, v47, s0
	v_lshl_add_u64 v[32:33], v[32:33], 1, v[68:69]
	global_store_short v[32:33], v34, off
	v_or_b32_e32 v34, 0x1000, v64
	v_add_u32_e32 v32, v34, v102
	v_ashrrev_i32_e32 v33, 31, v32
	v_cvt_pk_bf16_f32 v16, v16, s0
	v_lshl_add_u64 v[32:33], v[32:33], 1, v[68:69]
	global_store_short v[32:33], v16, off
	v_or_b32_e32 v33, 0x1080, v64
	v_add_u32_e32 v16, v33, v102
	v_cvt_pk_bf16_f32 v32, v17, s0
	v_ashrrev_i32_e32 v17, 31, v16
	v_lshl_add_u64 v[16:17], v[16:17], 1, v[68:69]
	global_store_short v[16:17], v32, off
	v_or_b32_e32 v32, 0x1100, v64
	v_add_u32_e32 v16, v32, v102
	v_ashrrev_i32_e32 v17, 31, v16
	v_cvt_pk_bf16_f32 v18, v18, s0
	v_lshl_add_u64 v[16:17], v[16:17], 1, v[68:69]
	global_store_short v[16:17], v18, off
	v_cvt_pk_bf16_f32 v18, v19, s0
	v_or_b32_e32 v19, 0x1180, v64
	v_add_u32_e32 v16, v19, v102
	v_ashrrev_i32_e32 v17, 31, v16
	v_lshl_add_u64 v[16:17], v[16:17], 1, v[68:69]
	global_store_short v[16:17], v18, off
	v_cvt_pk_bf16_f32 v18, v20, s0
	v_or_b32_e32 v20, 0x1400, v64
	v_add_u32_e32 v16, v20, v102
	v_ashrrev_i32_e32 v17, 31, v16
	v_lshl_add_u64 v[16:17], v[16:17], 1, v[68:69]
	global_store_short v[16:17], v18, off
	v_cvt_pk_bf16_f32 v18, v21, s0
	v_or_b32_e32 v21, 0x1480, v64
	v_add_u32_e32 v16, v21, v102
	v_ashrrev_i32_e32 v17, 31, v16
	v_lshl_add_u64 v[16:17], v[16:17], 1, v[68:69]
	global_store_short v[16:17], v18, off
	v_cvt_pk_bf16_f32 v18, v22, s0
	v_or_b32_e32 v22, 0x1500, v64
	v_add_u32_e32 v16, v22, v102
	v_ashrrev_i32_e32 v17, 31, v16
	v_lshl_add_u64 v[16:17], v[16:17], 1, v[68:69]
	global_store_short v[16:17], v18, off
	v_cvt_pk_bf16_f32 v18, v23, s0
	v_or_b32_e32 v23, 0x1580, v64
	v_add_u32_e32 v16, v23, v102
	v_ashrrev_i32_e32 v17, 31, v16
	v_lshl_add_u64 v[16:17], v[16:17], 1, v[68:69]
	global_store_short v[16:17], v18, off
	v_cvt_pk_bf16_f32 v18, v24, s0
	v_or_b32_e32 v24, 0x1800, v64
	v_add_u32_e32 v16, v24, v102
	v_ashrrev_i32_e32 v17, 31, v16
	v_lshl_add_u64 v[16:17], v[16:17], 1, v[68:69]
	global_store_short v[16:17], v18, off
	v_cvt_pk_bf16_f32 v18, v25, s0
	v_or_b32_e32 v25, 0x1880, v64
	v_add_u32_e32 v16, v25, v102
	v_ashrrev_i32_e32 v17, 31, v16
	v_lshl_add_u64 v[16:17], v[16:17], 1, v[68:69]
	global_store_short v[16:17], v18, off
	v_cvt_pk_bf16_f32 v18, v26, s0
	v_or_b32_e32 v26, 0x1900, v64
	v_add_u32_e32 v16, v26, v102
	v_ashrrev_i32_e32 v17, 31, v16
	v_lshl_add_u64 v[16:17], v[16:17], 1, v[68:69]
	global_store_short v[16:17], v18, off
	v_cvt_pk_bf16_f32 v18, v27, s0
	v_or_b32_e32 v27, 0x1980, v64
	v_add_u32_e32 v16, v27, v102
	v_ashrrev_i32_e32 v17, 31, v16
	v_lshl_add_u64 v[16:17], v[16:17], 1, v[68:69]
	global_store_short v[16:17], v18, off
	v_cvt_pk_bf16_f32 v18, v28, s0
	v_or_b32_e32 v28, 0x1c00, v64
	v_add_u32_e32 v16, v28, v102
	v_ashrrev_i32_e32 v17, 31, v16
	v_lshl_add_u64 v[16:17], v[16:17], 1, v[68:69]
	global_store_short v[16:17], v18, off
	v_cvt_pk_bf16_f32 v18, v29, s0
	v_or_b32_e32 v29, 0x1c80, v64
	v_add_u32_e32 v16, v29, v102
	v_ashrrev_i32_e32 v17, 31, v16
	v_lshl_add_u64 v[16:17], v[16:17], 1, v[68:69]
	global_store_short v[16:17], v18, off
	v_cvt_pk_bf16_f32 v18, v30, s0
	v_or_b32_e32 v30, 0x1d00, v64
	v_add_u32_e32 v16, v30, v102
	v_mfma_f32_32x32x16_bf16 v[0:15], v[72:75], v[96:99], v[0:15]
	v_ashrrev_i32_e32 v17, 31, v16
	v_lshl_add_u64 v[16:17], v[16:17], 1, v[68:69]
	global_store_short v[16:17], v18, off
	v_cvt_pk_bf16_f32 v18, v31, s0
	v_or_b32_e32 v31, 0x1d80, v64
	v_add_u32_e32 v16, v31, v102
	v_ashrrev_i32_e32 v17, 31, v16
	v_lshl_add_u64 v[16:17], v[16:17], 1, v[68:69]
	global_store_short v[16:17], v18, off
	v_add_u32_e32 v16, v34, v66
	v_ashrrev_i32_e32 v17, 31, v16
	s_nop 0
	v_cvt_pk_bf16_f32 v0, v0, s0
	v_lshl_add_u64 v[16:17], v[16:17], 1, v[68:69]
	global_store_short v[16:17], v0, off
	v_add_u32_e32 v0, v33, v66
	v_cvt_pk_bf16_f32 v16, v1, s0
	v_ashrrev_i32_e32 v1, 31, v0
	v_lshl_add_u64 v[0:1], v[0:1], 1, v[68:69]
	global_store_short v[0:1], v16, off
	v_add_u32_e32 v0, v32, v66
	v_ashrrev_i32_e32 v1, 31, v0
	v_cvt_pk_bf16_f32 v2, v2, s0
	v_lshl_add_u64 v[0:1], v[0:1], 1, v[68:69]
	global_store_short v[0:1], v2, off
	v_add_u32_e32 v0, v19, v66
	v_ashrrev_i32_e32 v1, 31, v0
	v_cvt_pk_bf16_f32 v2, v3, s0
	v_lshl_add_u64 v[0:1], v[0:1], 1, v[68:69]
	global_store_short v[0:1], v2, off
	v_add_u32_e32 v0, v20, v66
	v_ashrrev_i32_e32 v1, 31, v0
	v_cvt_pk_bf16_f32 v2, v4, s0
	v_lshl_add_u64 v[0:1], v[0:1], 1, v[68:69]
	global_store_short v[0:1], v2, off
	v_add_u32_e32 v0, v21, v66
	v_ashrrev_i32_e32 v1, 31, v0
	v_cvt_pk_bf16_f32 v2, v5, s0
	v_lshl_add_u64 v[0:1], v[0:1], 1, v[68:69]
	global_store_short v[0:1], v2, off
	v_add_u32_e32 v0, v22, v66
	v_ashrrev_i32_e32 v1, 31, v0
	v_cvt_pk_bf16_f32 v2, v6, s0
	v_lshl_add_u64 v[0:1], v[0:1], 1, v[68:69]
	global_store_short v[0:1], v2, off
	v_add_u32_e32 v0, v23, v66
	v_ashrrev_i32_e32 v1, 31, v0
	v_cvt_pk_bf16_f32 v2, v7, s0
	v_lshl_add_u64 v[0:1], v[0:1], 1, v[68:69]
	global_store_short v[0:1], v2, off
	v_add_u32_e32 v0, v24, v66
	v_ashrrev_i32_e32 v1, 31, v0
	v_cvt_pk_bf16_f32 v2, v8, s0
	v_lshl_add_u64 v[0:1], v[0:1], 1, v[68:69]
	global_store_short v[0:1], v2, off
	v_add_u32_e32 v0, v25, v66
	v_ashrrev_i32_e32 v1, 31, v0
	v_cvt_pk_bf16_f32 v2, v9, s0
	v_lshl_add_u64 v[0:1], v[0:1], 1, v[68:69]
	global_store_short v[0:1], v2, off
	v_add_u32_e32 v0, v26, v66
	v_ashrrev_i32_e32 v1, 31, v0
	v_cvt_pk_bf16_f32 v2, v10, s0
	v_lshl_add_u64 v[0:1], v[0:1], 1, v[68:69]
	global_store_short v[0:1], v2, off
	v_add_u32_e32 v0, v27, v66
	v_ashrrev_i32_e32 v1, 31, v0
	v_cvt_pk_bf16_f32 v2, v11, s0
	v_lshl_add_u64 v[0:1], v[0:1], 1, v[68:69]
	global_store_short v[0:1], v2, off
	v_add_u32_e32 v0, v28, v66
	v_ashrrev_i32_e32 v1, 31, v0
	v_cvt_pk_bf16_f32 v2, v12, s0
	v_lshl_add_u64 v[0:1], v[0:1], 1, v[68:69]
	global_store_short v[0:1], v2, off
	v_add_u32_e32 v0, v29, v66
	v_ashrrev_i32_e32 v1, 31, v0
	v_cvt_pk_bf16_f32 v2, v13, s0
	v_lshl_add_u64 v[0:1], v[0:1], 1, v[68:69]
	global_store_short v[0:1], v2, off
	v_add_u32_e32 v0, v30, v66
	v_ashrrev_i32_e32 v1, 31, v0
	v_cvt_pk_bf16_f32 v2, v14, s0
	v_lshl_add_u64 v[0:1], v[0:1], 1, v[68:69]
	global_store_short v[0:1], v2, off
	v_add_u32_e32 v0, v31, v66
	v_cvt_pk_bf16_f32 v2, v15, s0
	v_ashrrev_i32_e32 v1, 31, v0
	s_add_i32 s0, s4, 0x200
	s_xor_b32 s98, s98, 1
	v_lshl_add_u64 v[0:1], v[0:1], 1, v[68:69]
	s_cmpk_gt_i32 s4, 0x61f
	s_mov_b32 s4, s0
	global_store_short v[0:1], v2, off
	s_cbranch_scc1 .LBB0_696
